# v80 + guard: O-proj -> MLP-up hand-off additionally waits for all 256 workgroups to have left attention (MLP-up output buffer aliases Q/K/V)
# baseline (speedup 1.0000x reference)
.LBB0_1043:
	v_readlane_b32 s0, v254, 2
	s_add_i32 s4, s0, 2
	s_cmp_lt_i32 s4, s81
	s_cbranch_scc0 .LBB0_1109
	s_waitcnt vmcnt(0) lgkmcnt(0)
	s_barrier
	v_cmp_eq_u32_e32 vcc, 0, v215
	s_and_saveexec_b64 s[0:1], vcc
	s_cbranch_execz .Lp2p_w
	s_load_dwordx2 s[2:3], s[94:95], 0xb8
	v_readlane_b32 s101, v255, 12
	s_bfe_u32 s100, s101, 0x10002
	s_lshl_b32 s100, s100, 5
	s_lshr_b32 s6, s101, 3
	s_add_i32 s100, s100, s6
	s_lshl_b32 s100, s100, 5
	s_add_i32 s100, s100, 0x2c00
	s_and_b32 s6, s101, 7
	s_lshl_b32 s6, s6, 3
	s_bfe_u32 s7, s101, 0x30003
	s_add_i32 s6, s6, s7
	s_lshl_b32 s6, s6, 5
	s_add_i32 s6, s6, 0x2c00
	v_mov_b32_e32 v0, s100
	v_mov_b32_e32 v1, 1
	v_mov_b32_e32 v3, s6
	s_waitcnt lgkmcnt(0)
	s_add_u32 s2, s2, 0xe0000
	s_addc_u32 s3, s3, 0
	global_atomic_add v0, v1, s[2:3]
	v_mov_b32_e32 v4, 0x2c10
	global_atomic_add v4, v1, s[2:3]
	buffer_inv sc1
	s_mov_b32 s6, 0

.Lgs_i_1:
	v_mov_b32_e32 v0, 0x2c10
	s_mov_b32 s6, 0
.Lgs_q_1:
	global_load_dword v2, v0, s[2:3] sc1
	s_waitcnt vmcnt(0)
	v_cmp_le_u32_e32 vcc, 0x100, v2
	s_cbranch_vccnz .Lgs_r_1
	s_sleep 1
	s_add_i32 s6, s6, 1
	s_cmp_lt_u32 s6, 0x100000
	s_cbranch_scc1 .Lgs_q_1
